# gdn-prep D2-D4: second-product D-block read (and D2's second A pair) issued with the first operand batch; on top of prep6
# speedup vs baseline: 1.0054x; 1.0031x over previous
; #define LDS_BARRIER() asm volatile("s_waitcnt lgkmcnt(0)\n\ts_barrier" ::: "memory")
; __device__ __forceinline__ void gdn_prep_phase(const Frame& F0, const Args& a0, int l) {
;     ...
; #pragma unroll
;             for (int lev = 1; lev <= 3; ++lev) {
;                 const int nb = 4 - lev;
;                 if (wave < 2 * nb) { const int d = wave / nb, bj = wave % nb, bi = bj + lev;
;                     f32x4 t = (f32x4){0.f, 0.f, 0.f, 0.f};
; #pragma unroll
;                     for (int k = 0; k < 3; ++k) if (k < lev) { const int bk = bj + k;
; #pragma unroll
;                         for (int s = 0; s < 4; ++s) t = __builtin_amdgcn_mfma_f32_16x16x4f32(GD_AEL(d, 16 * bi + cc, 16 * bk + 4 * s + g), GD_MEL(d, 16 * bk + 4 * s + g, 16 * bj + cc), t, 0, 0, 0); }
;                     f32x4 m2 = (f32x4){0.f, 0.f, 0.f, 0.f};
; #pragma unroll
;                     for (int s = 0; s < 4; ++s) m2 = __builtin_amdgcn_mfma_f32_16x16x4f32(GD_MEL(d, 16 * bi + cc, 16 * bi + 4 * g + s), t[s], m2, 0, 0, 0);
; #pragma unroll
;                     for (int r = 0; r < 4; ++r) GD_MEL(d, 16 * bi + 4 * g + r, 16 * bj + cc) = -m2[r];
;                 }
;                 LDS_BARRIER();
;             }
.LBB0_440:
	s_or_b64 exec, exec, s[10:11]
	s_waitcnt lgkmcnt(0)
	s_barrier
	v_ashrrev_i32_e32 v110, 4, v108
	v_lshlrev_b32_e32 v21, 2, v110
	s_andn2_b64 vcc, exec, s[82:83]
	s_cbranch_vccnz .LBB0_442
	v_or_b32_e32 v22, s44, v109
	v_mul_lo_u32 v28, v22, s86
	v_add_u32_e32 v22, s60, v110
	v_lshlrev_b32_e32 v23, 2, v22
	v_readlane_b32 s10, v220, 42
	s_nop 1
	v_add3_u32 v23, s10, v28, v23
	v_add_u32_e32 v29, 0xcc00, v23
	ds_read2_b32 v[26:27], v29 offset1:4
	v_readlane_b32 s10, v220, 41
	s_nop 1
	v_add_u32_e32 v34, s10, v20
	v_mad_u64_u32 v[22:23], s[10:11], v22, s86, v[34:35]
	v_add_u32_e32 v35, s44, v21
	v_lshlrev_b32_e32 v254, 2, v35
	v_add3_u32 v254, s67, v28, v254
	ds_read_b32 v23, v22
	ds_read_b32 v30, v22 offset:1088
	ds_read_b32 v31, v22 offset:2176
	ds_read_b32 v32, v22 offset:3264
	ds_read2_b32 v[252:253], v29 offset0:8 offset1:12
	ds_read_b128 v[248:251], v254
	s_waitcnt lgkmcnt(0)
	v_mfma_f32_16x16x4_f32 v[22:25], v26, v23, 0
	v_mfma_f32_16x16x4_f32 v[22:25], v27, v30, v[22:25]
	v_mfma_f32_16x16x4_f32 v[22:25], v252, v31, v[22:25]
	v_mfma_f32_16x16x4_f32 v[22:25], v253, v32, v[22:25]
	s_nop 7
	s_nop 1
	v_mfma_f32_16x16x4_f32 v[30:33], v248, v22, 0
	v_mfma_f32_16x16x4_f32 v[30:33], v249, v23, v[30:33]
	v_mad_u64_u32 v[26:27], s[10:11], v35, s86, v[34:35]
	v_mfma_f32_16x16x4_f32 v[30:33], v250, v24, v[30:33]
	v_mfma_f32_16x16x4_f32 v[22:25], v251, v25, v[30:33]
	s_nop 9
	v_xor_b32_e32 v22, 0x80000000, v22
	v_xor_b32_e32 v23, 0x80000000, v23
	v_xor_b32_e32 v24, 0x80000000, v24
	v_xor_b32_e32 v25, 0x80000000, v25
	ds_write2_b32 v26, v22, v23 offset1:68
	ds_write2_b32 v26, v24, v25 offset0:136 offset1:204
.LBB0_442:
	s_waitcnt lgkmcnt(0)
	s_barrier
	s_and_b64 vcc, exec, s[8:9]
	s_cbranch_vccnz .LBB0_444
	v_or_b32_e32 v22, s50, v109
	v_mul_lo_u32 v32, v22, s86
	v_readlane_b32 s10, v220, 44
	v_add_u32_e32 v22, s61, v110
	v_lshlrev_b32_e32 v23, 2, v22
	v_add_u32_e32 v34, s10, v20
	v_readlane_b32 s10, v220, 43
	s_nop 1
	v_add3_u32 v23, s10, v32, v23
	v_mad_u64_u32 v[26:27], s[10:11], v22, s86, v[34:35]
	v_add_u32_e32 v27, 0xcc00, v23
	v_add_u32_e32 v35, s50, v21
	v_lshlrev_b32_e32 v254, 2, v35
	v_add3_u32 v254, s66, v32, v254
	ds_read_b32 v224, v26
	ds_read_b32 v225, v26 offset:1088
	ds_read_b32 v226, v26 offset:2176
	ds_read_b32 v227, v26 offset:3264
	ds_read_b32 v228, v26 offset:4352
	ds_read_b32 v229, v26 offset:5440
	ds_read_b32 v230, v26 offset:6528
	ds_read_b32 v231, v26 offset:7616
	ds_read2_b32 v[232:233], v27 offset1:4
	ds_read2_b32 v[234:235], v27 offset0:8 offset1:12
	ds_read2_b32 v[236:237], v27 offset0:16 offset1:20
	ds_read2_b32 v[238:239], v27 offset0:24 offset1:28
	ds_read_b128 v[248:251], v254
	s_waitcnt lgkmcnt(0)
	v_mfma_f32_16x16x4_f32 v[22:25], v232, v224, 0
	v_mfma_f32_16x16x4_f32 v[22:25], v233, v225, v[22:25]
	v_mfma_f32_16x16x4_f32 v[22:25], v234, v226, v[22:25]
	v_mfma_f32_16x16x4_f32 v[22:25], v235, v227, v[22:25]
	v_mfma_f32_16x16x4_f32 v[22:25], v236, v228, v[22:25]
	v_mfma_f32_16x16x4_f32 v[22:25], v237, v229, v[22:25]
	v_mfma_f32_16x16x4_f32 v[22:25], v238, v230, v[22:25]
	v_mfma_f32_16x16x4_f32 v[22:25], v239, v231, v[22:25]
	s_nop 7
	s_nop 1
	v_mfma_f32_16x16x4_f32 v[30:33], v248, v22, 0
	v_mfma_f32_16x16x4_f32 v[30:33], v249, v23, v[30:33]
	v_mad_u64_u32 v[26:27], s[10:11], v35, s86, v[34:35]
	v_mfma_f32_16x16x4_f32 v[30:33], v250, v24, v[30:33]
	v_mfma_f32_16x16x4_f32 v[22:25], v251, v25, v[30:33]
	s_nop 9
	v_xor_b32_e32 v22, 0x80000000, v22
	v_xor_b32_e32 v23, 0x80000000, v23
	ds_write2_b32 v26, v22, v23 offset1:68
	v_xor_b32_e32 v22, 0x80000000, v24
	v_xor_b32_e32 v23, 0x80000000, v25
	ds_write2_b32 v26, v22, v23 offset0:136 offset1:204
.LBB0_444:
	s_waitcnt lgkmcnt(0)
	s_barrier
	s_andn2_b64 vcc, exec, s[92:93]
	s_cbranch_vccnz .LBB0_446
	v_readlane_b32 s10, v220, 45
	v_add_u32_e32 v32, s47, v20
	s_nop 0
	v_mov_b32_e32 v22, s10
	v_mad_u32_u24 v22, v109, s86, v22
	v_add_u32_e32 v23, v22, v21
	v_mad_u64_u32 v[26:27], s[10:11], v110, s86, v[32:33]
	v_lshl_add_u32 v27, v110, 2, v22
	v_add_u32_e32 v30, 0xfc00, v27
	v_add_u32_e32 v33, 48, v21
	ds_read_b32 v252, v23 offset:65280
	ds_read_b32 v224, v26
	ds_read_b32 v225, v26 offset:1088
	ds_read_b32 v226, v26 offset:2176
	ds_read_b32 v227, v26 offset:3264
	ds_read_b32 v228, v26 offset:4352
	ds_read_b32 v229, v26 offset:5440
	ds_read2_b32 v[240:241], v30 offset0:196 offset1:200
	ds_read2_b32 v[242:243], v30 offset0:204 offset1:208
	ds_read2_b32 v[244:245], v30 offset0:212 offset1:216
	v_lshlrev_b32_e32 v21, 2, v33
	s_waitcnt lgkmcnt(0)
	ds_read_b32 v230, v26 offset:6528
	ds_read_b32 v231, v26 offset:7616
	ds_read_b32 v232, v26 offset:8704
	ds_read_b32 v233, v26 offset:9792
	ds_read_b32 v234, v26 offset:10880
	ds_read_b32 v235, v26 offset:11968
	ds_read2_b32 v[246:247], v30 offset0:220 offset1:224
	ds_read2_b32 v[248:249], v30 offset0:228 offset1:232
	ds_read_b32 v253, v27 offset:65456
	v_mfma_f32_16x16x4_f32 v[22:25], v252, v224, 0
	v_mfma_f32_16x16x4_f32 v[22:25], v240, v225, v[22:25]
	v_mfma_f32_16x16x4_f32 v[22:25], v241, v226, v[22:25]
	v_mfma_f32_16x16x4_f32 v[22:25], v242, v227, v[22:25]
	v_mfma_f32_16x16x4_f32 v[22:25], v243, v228, v[22:25]
	v_mfma_f32_16x16x4_f32 v[22:25], v244, v229, v[22:25]
	v_mul_u32_u24_e32 v27, 0x110, v109
	v_add3_u32 v27, s47, v27, v21
	ds_read_b128 v[236:239], v27 offset:13056
	s_waitcnt lgkmcnt(0)
	v_mfma_f32_16x16x4_f32 v[22:25], v245, v230, v[22:25]
	v_mfma_f32_16x16x4_f32 v[22:25], v246, v231, v[22:25]
	v_mfma_f32_16x16x4_f32 v[22:25], v247, v232, v[22:25]
	v_mfma_f32_16x16x4_f32 v[22:25], v248, v233, v[22:25]
	v_mfma_f32_16x16x4_f32 v[22:25], v249, v234, v[22:25]
	v_mfma_f32_16x16x4_f32 v[20:23], v253, v235, v[22:25]
	s_nop 7
	s_nop 1
	v_mfma_f32_16x16x4_f32 v[28:31], v236, v20, 0
	v_mfma_f32_16x16x4_f32 v[28:31], v237, v21, v[28:31]
	v_mad_u64_u32 v[24:25], s[10:11], v33, s86, v[32:33]
	v_mfma_f32_16x16x4_f32 v[28:31], v238, v22, v[28:31]
	v_mfma_f32_16x16x4_f32 v[20:23], v239, v23, v[28:31]
	s_nop 9
	v_xor_b32_e32 v20, 0x80000000, v20
	v_xor_b32_e32 v21, 0x80000000, v21
	v_xor_b32_e32 v22, 0x80000000, v22
	v_xor_b32_e32 v23, 0x80000000, v23
	ds_write2_b32 v24, v20, v21 offset1:68
	ds_write2_b32 v24, v22, v23 offset0:136 offset1:204
